# GEMM-up epilogue: conv weights for both column halves loaded early (first set at epilogue start, second set into accumulators that are already consumed)
# baseline (speedup 1.0000x reference)
; #define LAS __attribute__((address_space(3)))
;     __device__ __forceinline__ void operator()(const f32x4 (&acc)[2][2][4][2], const pg8::Unit& u, int wr, int wc, int fr, int fq) const {
;     ...
;         if (fr >= 14) {
; #pragma unroll
;             for (int ai = 0; ai < 2; ++ai)
; #pragma unroll
;                 for (int bj = 0; bj < 2; ++bj)
; #pragma unroll
;                     for (int n = 0; n < 2; ++n) *(LAS f32x4*)(xb + ((2 * ai + wr) * 2 + (fr - 14)) * 256 + bj * 128 + cc0 + 4 * n) = acc[ai][bj][3][n];
;             if (wr == 1) {
; #pragma unroll
;                 for (int bj = 0; bj < 2; ++bj)
; #pragma unroll
;                     for (int n = 0; n < 2; ++n) *(f32x4*)(halo + ((size_t)u.pm * 2 + (fr - 14)) * UPW + u.pn * 256 + bj * 128 + cc0 + 4 * n) = acc[1][bj][3][n];
;             }
;         }
;         if (wr == 0 && fr < 2) {
; #pragma unroll
;             for (int bj = 0; bj < 2; ++bj)
; #pragma unroll
;                 for (int n = 0; n < 2; ++n) *(f32x4*)(head + ((size_t)u.pm * 2 + fr) * UPW + u.pn * 256 + bj * 128 + cc0 + 4 * n) = acc[0][bj][0][n];
;         }
;         asm volatile("s_waitcnt lgkmcnt(0)" ::: "memory"); __builtin_amdgcn_s_barrier(); asm volatile("" ::: "memory");
;         const int row0 = u.pm * 256 + wr * 64 + fr;
;         u32x2 lo[2][4];
; #pragma unroll
;         for (int n = 0; n < 2; ++n) {
;             const int jg = u.pn * 128 + cc0 + 4 * n;
;             const f32x4 g0w = *(const f32x4*)(cw + jg), g1w = *(const f32x4*)(cw + UPW + jg), g2w = *(const f32x4*)(cw + 2 * UPW + jg), gb = *(const f32x4*)(cb + jg);
;             const f32x4 u0w = *(const f32x4*)(cw + DFF + jg), u1w = *(const f32x4*)(cw + UPW + DFF + jg), u2w = *(const f32x4*)(cw + 2 * UPW + DFF + jg), ub = *(const f32x4*)(cb + DFF + jg);
.LBB0_931:
	s_nop 7
	s_nop 7
	s_nop 7
	v_cndmask_b32_e64 v112, 0, 1, s[12:13]
	v_cmp_ne_u32_e64 s[6:7], 1, v112
	s_lshl_b32 s54, s76, 7
	v_or_b32_e32 v244, s54, v192
	v_lshlrev_b32_e32 v244, 2, v244
	v_readlane_b32 s84, v245, 13
	v_readlane_b32 s85, v245, 14
	v_readlane_b32 s86, v245, 15
	v_readlane_b32 s87, v245, 16
	s_nop 4
	global_load_dwordx4 v[148:151], v244, s[34:35]
	global_load_dwordx4 v[156:159], v244, s[86:87]
	global_load_dwordx4 v[132:135], v244, s[40:41]
	global_load_dwordx4 v[140:143], v244, s[42:43]
	global_load_dwordx4 v[152:155], v244, s[30:31]
	global_load_dwordx4 v[128:131], v244, s[38:39]
	global_load_dwordx4 v[144:147], v244, s[84:85]
	global_load_dwordx4 v[136:139], v244, s[36:37]
	v_cmp_eq_u32_e64 s[80:81], 15, v190
	s_and_saveexec_b64 s[8:9], s[80:81]
	s_cbranch_execz .Lupc2_a
	v_add_u32_e32 v112, 0xfffffc00, v213
	ds_write_b128 v112, v[108:111]
	ds_write_b128 v112, v[104:107] offset:1024
	ds_write_b128 v112, v[44:47] offset:16
	ds_write_b128 v112, v[40:43] offset:1040
	ds_write_b128 v112, v[100:103] offset:512
	ds_write_b128 v112, v[96:99] offset:1536
	ds_write_b128 v112, v[36:39] offset:528
	ds_write_b128 v112, v[32:35] offset:1552
	ds_write_b128 v112, v[76:79] offset:4096
	ds_write_b128 v112, v[72:75] offset:5120
	ds_write_b128 v112, v[12:15] offset:4112
	ds_write_b128 v112, v[8:11] offset:5136
	ds_write_b128 v112, v[68:71] offset:4608
	ds_write_b128 v112, v[64:67] offset:5632
	ds_write_b128 v112, v[4:7] offset:4624
	ds_write_b128 v112, v[0:3] offset:5648
	s_and_b64 vcc, exec, s[6:7]
	s_cbranch_vccnz .Lupc2_a
	s_ashr_i32 s53, s52, 31
	v_lshl_add_u64 v[112:113], s[52:53], 1, v[194:195]
	v_mov_b64_e32 v[126:127], s[18:19]
	s_lshl_b32 s54, s76, 8
	v_mad_u64_u32 v[126:127], s[78:79], v112, s74, v[126:127]
	s_ashr_i32 s55, s54, 31
	v_mad_i32_i24 v127, v113, s74, v127
	v_lshl_add_u64 v[112:113], s[54:55], 2, v[126:127]
	v_lshlrev_b32_e32 v126, 2, v192
	v_mov_b32_e32 v127, v189
	v_lshl_add_u64 v[112:113], v[112:113], 0, v[126:127]
	s_mov_b32 s82, 0xffff5000
	s_mov_b32 s83, -1
	v_lshl_add_u64 v[126:127], v[112:113], 0, s[82:83]
	global_store_dwordx4 v[126:127], v[76:79], off
	global_store_dwordx4 v[112:113], v[72:75], off
	global_store_dwordx4 v[126:127], v[12:15], off offset:16
	global_store_dwordx4 v[112:113], v[8:11], off offset:16
	global_store_dwordx4 v[126:127], v[68:71], off offset:512
	global_store_dwordx4 v[112:113], v[64:67], off offset:512
	global_store_dwordx4 v[126:127], v[4:7], off offset:528
	global_store_dwordx4 v[112:113], v[0:3], off offset:528

;     __device__ __forceinline__ void operator()(const f32x4 (&acc)[2][2][4][2], const pg8::Unit& u, int wr, int wc, int fr, int fq) const {
;     ...
;         asm volatile("s_waitcnt lgkmcnt(0)" ::: "memory"); __builtin_amdgcn_s_barrier(); asm volatile("" ::: "memory");
;         const int row0 = u.pm * 256 + wr * 64 + fr;
;         u32x2 lo[2][4];
; #pragma unroll
;         for (int n = 0; n < 2; ++n) {
;             const int jg = u.pn * 128 + cc0 + 4 * n;
;             const f32x4 g0w = *(const f32x4*)(cw + jg), g1w = *(const f32x4*)(cw + UPW + jg), g2w = *(const f32x4*)(cw + 2 * UPW + jg), gb = *(const f32x4*)(cb + jg);
;             const f32x4 u0w = *(const f32x4*)(cw + DFF + jg), u1w = *(const f32x4*)(cw + UPW + DFF + jg), u2w = *(const f32x4*)(cw + 2 * UPW + DFF + jg), ub = *(const f32x4*)(cb + DFF + jg);
; #pragma unroll
;             for (int ai = 0; ai < 2; ++ai) {
;                 const int gi = 2 * ai + wr;
;                 f32x4 pg1 = (f32x4){0.f, 0.f, 0.f, 0.f}, pg2 = pg1, pu1 = pg1, pu2 = pg1;
;                 if (gi > 0) {
;                     const LAS float* xp = xb + ((gi - 1) * 2) * 256 + cc0 + 4 * n;
;                     pg1 = *(const LAS f32x4*)(xp + 256); pu1 = *(const LAS f32x4*)(xp + 256 + 128);
;                     pg2 = *(const LAS f32x4*)(xp + (fr & 1) * 256); pu2 = *(const LAS f32x4*)(xp + (fr & 1) * 256 + 128);
;                 }
; #pragma unroll
;                 for (int m = 0; m < 4; ++m) {
;                     float a[4];
; #pragma unroll
;                     for (int e = 0; e < 4; ++e) {
;                         const float gc = acc[ai][0][m][n][e], uc = acc[ai][1][m][n][e];
;                         float og1, og2, ou1, ou2;
;                         if (m == 0) { og1 = pg1[e]; og2 = pg2[e]; ou1 = pu1[e]; ou2 = pu2[e]; }
;                         else { const float gp = acc[ai][0][m - 1][n][e], up = acc[ai][1][m - 1][n][e]; og1 = dpp_ror1(gp); og2 = dpp_ror2(gp); ou1 = dpp_ror1(up); ou2 = dpp_ror2(up); }
;                         const float gm1 = dpp_shr1(og1, gc), gm2 = dpp_shr2(og2, gc), um1 = dpp_shr1(ou1, uc), um2 = dpp_shr2(ou2, uc);
;                         const float yg = g0w[e] * gm2 + g1w[e] * gm1 + g2w[e] * gc + gb[e];
;                         const float yu = u0w[e] * um2 + u1w[e] * um1 + u2w[e] * uc + ub[e];
;                         a[e] = fast_silu(yg) * yu;
;                     }
.Lupc2_b:
	s_or_b64 exec, exec, s[8:9]
	s_lshl_b32 s54, s76, 7
	s_waitcnt lgkmcnt(0)
	s_barrier
	s_lshl_b32 s2, s52, 8
	v_mad_u32_u24 v243, v190, 3, v193
	v_add_u32_e32 v243, s2, v243
	v_mul_u32_u24_e32 v243, 0x2c00, v243
	s_lshl_b32 s2, s54, 1
	v_add3_u32 v243, v243, s2, v188
	v_mov_b32_e32 v126, 0xbfb8aa3b
	v_mov_b32_e32 v127, 0xbfb8aa3b
	v_cmp_ne_u32_e64 s[78:79], 0, v190
	s_nop 3
	s_or_b64 s[78:79], s[78:79], s[24:25]
	v_mov_b32_e32 v172, 0
	v_mov_b32_e32 v173, 0
	v_mov_b32_e32 v174, 0
	v_mov_b32_e32 v175, 0
	v_mov_b32_e32 v164, 0
	v_mov_b32_e32 v165, 0
	v_mov_b32_e32 v166, 0
	v_mov_b32_e32 v167, 0
	v_mov_b32_e32 v176, 0
	v_mov_b32_e32 v177, 0
	v_mov_b32_e32 v178, 0
	v_mov_b32_e32 v179, 0
	v_mov_b32_e32 v168, 0
	v_mov_b32_e32 v169, 0
	v_mov_b32_e32 v170, 0
	v_mov_b32_e32 v171, 0
	s_andn2_b64 vcc, exec, s[24:25]
	s_cbranch_vccnz .Lupc2_nocarry00
	ds_read_b128 v[172:175], v215 offset:1024
	ds_read_b128 v[164:167], v215 offset:1536
	ds_read_b128 v[176:179], v215
	ds_read_b128 v[168:171], v215 offset:512
.Lupc2_nocarry00:
	s_waitcnt vmcnt(0) lgkmcnt(0)
	v_mov_b32_dpp v172, v104 row_shr:1 row_mask:0xf bank_mask:0xf
	v_mov_b32_dpp v176, v108 row_shr:1 row_mask:0xf bank_mask:0xf
	v_mov_b32_dpp v164, v96 row_shr:1 row_mask:0xf bank_mask:0xf
	v_mov_b32_dpp v168, v100 row_shr:1 row_mask:0xf bank_mask:0xf
	v_mov_b32_dpp v173, v105 row_shr:1 row_mask:0xf bank_mask:0xf
	v_mov_b32_dpp v177, v109 row_shr:1 row_mask:0xf bank_mask:0xf
	v_mov_b32_dpp v165, v97 row_shr:1 row_mask:0xf bank_mask:0xf
	v_mov_b32_dpp v169, v101 row_shr:1 row_mask:0xf bank_mask:0xf
	v_mov_b32_dpp v174, v106 row_shr:1 row_mask:0xf bank_mask:0xf
	v_mov_b32_dpp v178, v110 row_shr:1 row_mask:0xf bank_mask:0xf
	v_mov_b32_dpp v166, v98 row_shr:1 row_mask:0xf bank_mask:0xf
	v_mov_b32_dpp v170, v102 row_shr:1 row_mask:0xf bank_mask:0xf
	v_mov_b32_dpp v175, v107 row_shr:1 row_mask:0xf bank_mask:0xf
	v_mov_b32_dpp v179, v111 row_shr:1 row_mask:0xf bank_mask:0xf
	v_mov_b32_dpp v167, v99 row_shr:1 row_mask:0xf bank_mask:0xf
	v_mov_b32_dpp v171, v103 row_shr:1 row_mask:0xf bank_mask:0xf
	v_pk_fma_f32 v[204:205], v[148:149], v[104:105], v[156:157]
	v_pk_fma_f32 v[112:113], v[132:133], v[96:97], v[140:141]
	v_pk_fma_f32 v[206:207], v[150:151], v[106:107], v[158:159]
	v_pk_fma_f32 v[210:211], v[134:135], v[98:99], v[142:143]
	v_pk_fma_f32 v[204:205], v[152:153], v[108:109], v[204:205]
	v_pk_fma_f32 v[112:113], v[128:129], v[100:101], v[112:113]
	v_pk_fma_f32 v[206:207], v[154:155], v[110:111], v[206:207]
	v_pk_fma_f32 v[210:211], v[130:131], v[102:103], v[210:211]
	v_pk_fma_f32 v[204:205], v[144:145], v[122:123], v[204:205]
	v_pk_fma_f32 v[112:113], v[136:137], v[118:119], v[112:113]
	v_pk_fma_f32 v[206:207], v[146:147], v[124:125], v[206:207]
	v_pk_fma_f32 v[210:211], v[138:139], v[120:121], v[210:211]
	v_pk_mul_f32 v[226:227], v[204:205], v[126:127]
	v_pk_mul_f32 v[228:229], v[206:207], v[126:127]
	v_exp_f32_e32 v226, v226
	v_exp_f32_e32 v227, v227
	v_exp_f32_e32 v228, v228
	v_exp_f32_e32 v229, v229
	s_nop 0
	v_pk_add_f32 v[226:227], v[226:227], 1.0 op_sel_hi:[1,0]
	v_pk_add_f32 v[228:229], v[228:229], 1.0 op_sel_hi:[1,0]
	v_rcp_f32_e32 v226, v226
	v_rcp_f32_e32 v227, v227
	v_rcp_f32_e32 v228, v228
	v_rcp_f32_e32 v229, v229
	s_nop 0
	v_pk_mul_f32 v[204:205], v[204:205], v[226:227]
	v_pk_mul_f32 v[206:207], v[206:207], v[228:229]
	v_pk_mul_f32 v[204:205], v[204:205], v[112:113]
	v_pk_mul_f32 v[206:207], v[206:207], v[210:211]
	v_cvt_pk_bf16_f32 v104, v204, v205
	v_cvt_pk_bf16_f32 v105, v206, v207
	v_pk_fma_f32 v[204:205], v[148:149], v[108:109], v[156:157]
	v_pk_fma_f32 v[112:113], v[132:133], v[100:101], v[140:141]
	v_pk_fma_f32 v[206:207], v[150:151], v[110:111], v[158:159]
	v_pk_fma_f32 v[210:211], v[134:135], v[102:103], v[142:143]
	v_pk_fma_f32 v[204:205], v[152:153], v[122:123], v[204:205]
	v_pk_fma_f32 v[112:113], v[128:129], v[118:119], v[112:113]
	v_pk_fma_f32 v[206:207], v[154:155], v[124:125], v[206:207]
	v_pk_fma_f32 v[210:211], v[130:131], v[120:121], v[210:211]
	v_pk_fma_f32 v[204:205], v[144:145], v[160:161], v[204:205]
	v_pk_fma_f32 v[112:113], v[136:137], v[114:115], v[112:113]
	v_pk_fma_f32 v[206:207], v[146:147], v[162:163], v[206:207]
	v_pk_fma_f32 v[210:211], v[138:139], v[116:117], v[210:211]
	v_pk_mul_f32 v[226:227], v[204:205], v[126:127]
	v_pk_mul_f32 v[228:229], v[206:207], v[126:127]
	v_exp_f32_e32 v226, v226
	v_exp_f32_e32 v227, v227
	v_exp_f32_e32 v228, v228
	v_exp_f32_e32 v229, v229
	s_nop 0
	v_pk_add_f32 v[226:227], v[226:227], 1.0 op_sel_hi:[1,0]
	v_pk_add_f32 v[228:229], v[228:229], 1.0 op_sel_hi:[1,0]
	v_rcp_f32_e32 v226, v226
	v_rcp_f32_e32 v227, v227
	v_rcp_f32_e32 v228, v228
	v_rcp_f32_e32 v229, v229
	s_nop 0
	v_pk_mul_f32 v[204:205], v[204:205], v[226:227]
	v_pk_mul_f32 v[206:207], v[206:207], v[228:229]
	v_pk_mul_f32 v[204:205], v[204:205], v[112:113]
	v_pk_mul_f32 v[206:207], v[206:207], v[210:211]
	v_cvt_pk_bf16_f32 v108, v204, v205
	v_cvt_pk_bf16_f32 v109, v206, v207
	v_pk_fma_f32 v[204:205], v[148:149], v[122:123], v[156:157]
	v_pk_fma_f32 v[112:113], v[132:133], v[118:119], v[140:141]
	v_pk_fma_f32 v[206:207], v[150:151], v[124:125], v[158:159]
	v_pk_fma_f32 v[210:211], v[134:135], v[120:121], v[142:143]
	v_pk_fma_f32 v[204:205], v[152:153], v[160:161], v[204:205]
	v_pk_fma_f32 v[112:113], v[128:129], v[114:115], v[112:113]
	v_pk_fma_f32 v[206:207], v[154:155], v[162:163], v[206:207]
	v_pk_fma_f32 v[210:211], v[130:131], v[116:117], v[210:211]
	v_pk_fma_f32 v[204:205], v[144:145], v[172:173], v[204:205]
	v_pk_fma_f32 v[112:113], v[136:137], v[164:165], v[112:113]
	v_pk_fma_f32 v[206:207], v[146:147], v[174:175], v[206:207]
; #define LAS __attribute__((address_space(3)))
;     __device__ __forceinline__ void operator()(const f32x4 (&acc)[2][2][4][2], const pg8::Unit& u, int wr, int wc, int fr, int fq) const {
;     ...
;         for (int n = 0; n < 2; ++n) {
;             const int jg = u.pn * 128 + cc0 + 4 * n;
;             const f32x4 g0w = *(const f32x4*)(cw + jg), g1w = *(const f32x4*)(cw + UPW + jg), g2w = *(const f32x4*)(cw + 2 * UPW + jg), gb = *(const f32x4*)(cb + jg);
;             const f32x4 u0w = *(const f32x4*)(cw + DFF + jg), u1w = *(const f32x4*)(cw + UPW + DFF + jg), u2w = *(const f32x4*)(cw + 2 * UPW + DFF + jg), ub = *(const f32x4*)(cb + DFF + jg);
; #pragma unroll
;             for (int ai = 0; ai < 2; ++ai) {
;                 const int gi = 2 * ai + wr;
;                 f32x4 pg1 = (f32x4){0.f, 0.f, 0.f, 0.f}, pg2 = pg1, pu1 = pg1, pu2 = pg1;
;                 if (gi > 0) {
;                     const LAS float* xp = xb + ((gi - 1) * 2) * 256 + cc0 + 4 * n;
;                     pg1 = *(const LAS f32x4*)(xp + 256); pu1 = *(const LAS f32x4*)(xp + 256 + 128);
;                     pg2 = *(const LAS f32x4*)(xp + (fr & 1) * 256); pu2 = *(const LAS f32x4*)(xp + (fr & 1) * 256 + 128);
;                 }
; #pragma unroll
;                 for (int m = 0; m < 4; ++m) {
;                     float a[4];
; #pragma unroll
;                     for (int e = 0; e < 4; ++e) {
;                         const float gc = acc[ai][0][m][n][e], uc = acc[ai][1][m][n][e];
;                         float og1, og2, ou1, ou2;
;                         if (m == 0) { og1 = pg1[e]; og2 = pg2[e]; ou1 = pu1[e]; ou2 = pu2[e]; }
;                         else { const float gp = acc[ai][0][m - 1][n][e], up = acc[ai][1][m - 1][n][e]; og1 = dpp_ror1(gp); og2 = dpp_ror2(gp); ou1 = dpp_ror1(up); ou2 = dpp_ror2(up); }
;                         const float gm1 = dpp_shr1(og1, gc), gm2 = dpp_shr2(og2, gc), um1 = dpp_shr1(ou1, uc), um2 = dpp_shr2(ou2, uc);
;                         const float yg = g0w[e] * gm2 + g1w[e] * gm1 + g2w[e] * gc + gb[e];
;                         const float yu = u0w[e] * um2 + u1w[e] * um1 + u2w[e] * uc + ub[e];
;                         a[e] = fast_silu(yg) * yu;
;                     }
;                     u32x2 pk; pk.x = cvt_pk_bf16(a[0], a[1]); pk.y = cvt_pk_bf16(a[2], a[3]);
;                     if (n == 0) lo[ai][m] = pk;
	v_pk_fma_f32 v[210:211], v[138:139], v[166:167], v[210:211]
	v_pk_mul_f32 v[226:227], v[204:205], v[126:127]
	v_pk_mul_f32 v[228:229], v[206:207], v[126:127]
	v_exp_f32_e32 v226, v226
	v_exp_f32_e32 v227, v227
	v_exp_f32_e32 v228, v228
	v_exp_f32_e32 v229, v229
	s_nop 0
	v_pk_add_f32 v[226:227], v[226:227], 1.0 op_sel_hi:[1,0]
	v_pk_add_f32 v[228:229], v[228:229], 1.0 op_sel_hi:[1,0]
	v_rcp_f32_e32 v226, v226
	v_rcp_f32_e32 v227, v227
	v_rcp_f32_e32 v228, v228
	v_rcp_f32_e32 v229, v229
	s_nop 0
	v_pk_mul_f32 v[204:205], v[204:205], v[226:227]
	v_pk_mul_f32 v[206:207], v[206:207], v[228:229]
	v_pk_mul_f32 v[204:205], v[204:205], v[112:113]
	v_pk_mul_f32 v[206:207], v[206:207], v[210:211]
	v_cvt_pk_bf16_f32 v122, v204, v205
	v_cvt_pk_bf16_f32 v123, v206, v207
	v_pk_fma_f32 v[204:205], v[148:149], v[160:161], v[156:157]
	v_pk_fma_f32 v[112:113], v[132:133], v[114:115], v[140:141]
	v_pk_fma_f32 v[206:207], v[150:151], v[162:163], v[158:159]
	v_pk_fma_f32 v[210:211], v[134:135], v[116:117], v[142:143]
	v_pk_fma_f32 v[204:205], v[152:153], v[172:173], v[204:205]
	v_pk_fma_f32 v[112:113], v[128:129], v[164:165], v[112:113]
	v_pk_fma_f32 v[206:207], v[154:155], v[174:175], v[206:207]
	v_pk_fma_f32 v[210:211], v[130:131], v[166:167], v[210:211]
	v_pk_fma_f32 v[204:205], v[144:145], v[176:177], v[204:205]
	v_pk_fma_f32 v[112:113], v[136:137], v[168:169], v[112:113]
	v_pk_fma_f32 v[206:207], v[146:147], v[178:179], v[206:207]
	v_pk_fma_f32 v[210:211], v[138:139], v[170:171], v[210:211]
	v_pk_mul_f32 v[226:227], v[204:205], v[126:127]
	v_pk_mul_f32 v[228:229], v[206:207], v[126:127]
	v_exp_f32_e32 v226, v226
	v_exp_f32_e32 v227, v227
	v_exp_f32_e32 v228, v228
	v_exp_f32_e32 v229, v229
	s_nop 0
	v_pk_add_f32 v[226:227], v[226:227], 1.0 op_sel_hi:[1,0]
	v_pk_add_f32 v[228:229], v[228:229], 1.0 op_sel_hi:[1,0]
	v_rcp_f32_e32 v226, v226
	v_rcp_f32_e32 v227, v227
	v_rcp_f32_e32 v228, v228
	v_rcp_f32_e32 v229, v229
	s_nop 0
	v_pk_mul_f32 v[204:205], v[204:205], v[226:227]
	v_pk_mul_f32 v[206:207], v[206:207], v[228:229]
	v_pk_mul_f32 v[204:205], v[204:205], v[112:113]
	v_pk_mul_f32 v[206:207], v[206:207], v[210:211]
	v_cvt_pk_bf16_f32 v160, v204, v205
	v_cvt_pk_bf16_f32 v161, v206, v207
	global_load_dwordx4 v[114:117], v244, s[34:35] offset:16
	global_load_dwordx4 v[118:121], v244, s[86:87] offset:16
	global_load_dwordx4 v[100:103], v244, s[40:41] offset:16
	global_load_dwordx4 v[96:99], v244, s[42:43] offset:16
	global_load_dwordx4 v[230:233], v244, s[30:31] offset:16
	global_load_dwordx4 v[234:237], v244, s[38:39] offset:16
	global_load_dwordx4 v[238:241], v244, s[84:85] offset:16
	ds_read_b128 v[172:175], v215 offset:5120
	ds_read_b128 v[164:167], v215 offset:5632
	ds_read_b128 v[176:179], v215 offset:4096
	ds_read_b128 v[168:171], v215 offset:4608
	s_waitcnt lgkmcnt(0)
	v_mov_b32_dpp v172, v72 row_shr:1 row_mask:0xf bank_mask:0xf
	v_mov_b32_dpp v176, v76 row_shr:1 row_mask:0xf bank_mask:0xf
	v_mov_b32_dpp v164, v64 row_shr:1 row_mask:0xf bank_mask:0xf
	v_mov_b32_dpp v168, v68 row_shr:1 row_mask:0xf bank_mask:0xf
	v_mov_b32_dpp v173, v73 row_shr:1 row_mask:0xf bank_mask:0xf
	v_mov_b32_dpp v177, v77 row_shr:1 row_mask:0xf bank_mask:0xf
	v_mov_b32_dpp v165, v65 row_shr:1 row_mask:0xf bank_mask:0xf
	v_mov_b32_dpp v169, v69 row_shr:1 row_mask:0xf bank_mask:0xf
	v_mov_b32_dpp v174, v74 row_shr:1 row_mask:0xf bank_mask:0xf
	v_mov_b32_dpp v178, v78 row_shr:1 row_mask:0xf bank_mask:0xf
	v_mov_b32_dpp v166, v66 row_shr:1 row_mask:0xf bank_mask:0xf
	v_mov_b32_dpp v170, v70 row_shr:1 row_mask:0xf bank_mask:0xf
	v_mov_b32_dpp v175, v75 row_shr:1 row_mask:0xf bank_mask:0xf
	v_mov_b32_dpp v179, v79 row_shr:1 row_mask:0xf bank_mask:0xf
	v_mov_b32_dpp v167, v67 row_shr:1 row_mask:0xf bank_mask:0xf
	v_mov_b32_dpp v171, v71 row_shr:1 row_mask:0xf bank_mask:0xf
	v_pk_fma_f32 v[204:205], v[148:149], v[72:73], v[156:157]
	v_pk_fma_f32 v[112:113], v[132:133], v[64:65], v[140:141]
	v_pk_fma_f32 v[206:207], v[150:151], v[74:75], v[158:159]
	v_pk_fma_f32 v[210:211], v[134:135], v[66:67], v[142:143]
	v_pk_fma_f32 v[204:205], v[152:153], v[76:77], v[204:205]
	v_pk_fma_f32 v[112:113], v[128:129], v[68:69], v[112:113]
	v_pk_fma_f32 v[206:207], v[154:155], v[78:79], v[206:207]
	v_pk_fma_f32 v[210:211], v[130:131], v[70:71], v[210:211]
	v_pk_fma_f32 v[204:205], v[144:145], v[84:85], v[204:205]
	v_pk_fma_f32 v[112:113], v[136:137], v[80:81], v[112:113]
	v_pk_fma_f32 v[206:207], v[146:147], v[86:87], v[206:207]
	v_pk_fma_f32 v[210:211], v[138:139], v[82:83], v[210:211]
	v_pk_mul_f32 v[226:227], v[204:205], v[126:127]
	v_pk_mul_f32 v[228:229], v[206:207], v[126:127]
	v_exp_f32_e32 v226, v226
	v_exp_f32_e32 v227, v227
	v_exp_f32_e32 v228, v228
	v_exp_f32_e32 v229, v229
	s_nop 0
	v_pk_add_f32 v[226:227], v[226:227], 1.0 op_sel_hi:[1,0]
	v_pk_add_f32 v[228:229], v[228:229], 1.0 op_sel_hi:[1,0]
	v_rcp_f32_e32 v226, v226
	v_rcp_f32_e32 v227, v227
	v_rcp_f32_e32 v228, v228
	v_rcp_f32_e32 v229, v229
	s_nop 0
	v_pk_mul_f32 v[204:205], v[204:205], v[226:227]
	v_pk_mul_f32 v[206:207], v[206:207], v[228:229]
	v_pk_mul_f32 v[204:205], v[204:205], v[112:113]
	v_pk_mul_f32 v[206:207], v[206:207], v[210:211]
	v_cvt_pk_bf16_f32 v72, v204, v205
	v_cvt_pk_bf16_f32 v73, v206, v207
	v_pk_fma_f32 v[204:205], v[148:149], v[76:77], v[156:157]
	v_pk_fma_f32 v[112:113], v[132:133], v[68:69], v[140:141]
	v_pk_fma_f32 v[206:207], v[150:151], v[78:79], v[158:159]
	v_pk_fma_f32 v[210:211], v[134:135], v[70:71], v[142:143]
	v_pk_fma_f32 v[204:205], v[152:153], v[84:85], v[204:205]
	v_pk_fma_f32 v[112:113], v[128:129], v[80:81], v[112:113]
	v_pk_fma_f32 v[206:207], v[154:155], v[86:87], v[206:207]
; #define LAS __attribute__((address_space(3)))
;     __device__ __forceinline__ void operator()(const f32x4 (&acc)[2][2][4][2], const pg8::Unit& u, int wr, int wc, int fr, int fq) const {
;     ...
;         for (int n = 0; n < 2; ++n) {
;             const int jg = u.pn * 128 + cc0 + 4 * n;
;             const f32x4 g0w = *(const f32x4*)(cw + jg), g1w = *(const f32x4*)(cw + UPW + jg), g2w = *(const f32x4*)(cw + 2 * UPW + jg), gb = *(const f32x4*)(cb + jg);
;             const f32x4 u0w = *(const f32x4*)(cw + DFF + jg), u1w = *(const f32x4*)(cw + UPW + DFF + jg), u2w = *(const f32x4*)(cw + 2 * UPW + DFF + jg), ub = *(const f32x4*)(cb + DFF + jg);
; #pragma unroll
;             for (int ai = 0; ai < 2; ++ai) {
;                 const int gi = 2 * ai + wr;
;                 f32x4 pg1 = (f32x4){0.f, 0.f, 0.f, 0.f}, pg2 = pg1, pu1 = pg1, pu2 = pg1;
;                 if (gi > 0) {
;                     const LAS float* xp = xb + ((gi - 1) * 2) * 256 + cc0 + 4 * n;
;                     pg1 = *(const LAS f32x4*)(xp + 256); pu1 = *(const LAS f32x4*)(xp + 256 + 128);
;                     pg2 = *(const LAS f32x4*)(xp + (fr & 1) * 256); pu2 = *(const LAS f32x4*)(xp + (fr & 1) * 256 + 128);
;                 }
; #pragma unroll
;                 for (int m = 0; m < 4; ++m) {
;                     float a[4];
; #pragma unroll
;                     for (int e = 0; e < 4; ++e) {
;                         const float gc = acc[ai][0][m][n][e], uc = acc[ai][1][m][n][e];
;                         float og1, og2, ou1, ou2;
;                         if (m == 0) { og1 = pg1[e]; og2 = pg2[e]; ou1 = pu1[e]; ou2 = pu2[e]; }
;                         else { const float gp = acc[ai][0][m - 1][n][e], up = acc[ai][1][m - 1][n][e]; og1 = dpp_ror1(gp); og2 = dpp_ror2(gp); ou1 = dpp_ror1(up); ou2 = dpp_ror2(up); }
;                         const float gm1 = dpp_shr1(og1, gc), gm2 = dpp_shr2(og2, gc), um1 = dpp_shr1(ou1, uc), um2 = dpp_shr2(ou2, uc);
;                         const float yg = g0w[e] * gm2 + g1w[e] * gm1 + g2w[e] * gc + gb[e];
;                         const float yu = u0w[e] * um2 + u1w[e] * um1 + u2w[e] * uc + ub[e];
;                         a[e] = fast_silu(yg) * yu;
;                     }
;                     u32x2 pk; pk.x = cvt_pk_bf16(a[0], a[1]); pk.y = cvt_pk_bf16(a[2], a[3]);
;                     if (n == 0) lo[ai][m] = pk;
	v_pk_fma_f32 v[210:211], v[130:131], v[82:83], v[210:211]
	v_pk_fma_f32 v[204:205], v[144:145], v[92:93], v[204:205]
	v_pk_fma_f32 v[112:113], v[136:137], v[88:89], v[112:113]
	v_pk_fma_f32 v[206:207], v[146:147], v[94:95], v[206:207]
	v_pk_fma_f32 v[210:211], v[138:139], v[90:91], v[210:211]
	v_pk_mul_f32 v[226:227], v[204:205], v[126:127]
	v_pk_mul_f32 v[228:229], v[206:207], v[126:127]
	v_exp_f32_e32 v226, v226
	v_exp_f32_e32 v227, v227
	v_exp_f32_e32 v228, v228
	v_exp_f32_e32 v229, v229
	s_nop 0
	v_pk_add_f32 v[226:227], v[226:227], 1.0 op_sel_hi:[1,0]
	v_pk_add_f32 v[228:229], v[228:229], 1.0 op_sel_hi:[1,0]
	v_rcp_f32_e32 v226, v226
	v_rcp_f32_e32 v227, v227
	v_rcp_f32_e32 v228, v228
	v_rcp_f32_e32 v229, v229
	s_nop 0
	v_pk_mul_f32 v[204:205], v[204:205], v[226:227]
	v_pk_mul_f32 v[206:207], v[206:207], v[228:229]
	v_pk_mul_f32 v[204:205], v[204:205], v[112:113]
	v_pk_mul_f32 v[206:207], v[206:207], v[210:211]
	v_cvt_pk_bf16_f32 v76, v204, v205
	v_cvt_pk_bf16_f32 v77, v206, v207
	v_pk_fma_f32 v[204:205], v[148:149], v[84:85], v[156:157]
	v_pk_fma_f32 v[112:113], v[132:133], v[80:81], v[140:141]
	v_pk_fma_f32 v[206:207], v[150:151], v[86:87], v[158:159]
	v_pk_fma_f32 v[210:211], v[134:135], v[82:83], v[142:143]
	v_pk_fma_f32 v[204:205], v[152:153], v[92:93], v[204:205]
	v_pk_fma_f32 v[112:113], v[128:129], v[88:89], v[112:113]
	v_pk_fma_f32 v[206:207], v[154:155], v[94:95], v[206:207]
	v_pk_fma_f32 v[210:211], v[130:131], v[90:91], v[210:211]
	v_pk_fma_f32 v[204:205], v[144:145], v[172:173], v[204:205]
	v_pk_fma_f32 v[112:113], v[136:137], v[164:165], v[112:113]
	v_pk_fma_f32 v[206:207], v[146:147], v[174:175], v[206:207]
	v_pk_fma_f32 v[210:211], v[138:139], v[166:167], v[210:211]
	v_pk_mul_f32 v[226:227], v[204:205], v[126:127]
	v_pk_mul_f32 v[228:229], v[206:207], v[126:127]
	v_exp_f32_e32 v226, v226
	v_exp_f32_e32 v227, v227
	v_exp_f32_e32 v228, v228
	v_exp_f32_e32 v229, v229
	s_nop 0
	v_pk_add_f32 v[226:227], v[226:227], 1.0 op_sel_hi:[1,0]
	v_pk_add_f32 v[228:229], v[228:229], 1.0 op_sel_hi:[1,0]
	v_rcp_f32_e32 v226, v226
	v_rcp_f32_e32 v227, v227
	v_rcp_f32_e32 v228, v228
	v_rcp_f32_e32 v229, v229
	s_nop 0
	v_pk_mul_f32 v[204:205], v[204:205], v[226:227]
	v_pk_mul_f32 v[206:207], v[206:207], v[228:229]
	v_pk_mul_f32 v[204:205], v[204:205], v[112:113]
	v_pk_mul_f32 v[206:207], v[206:207], v[210:211]
	v_cvt_pk_bf16_f32 v84, v204, v205
	v_cvt_pk_bf16_f32 v85, v206, v207
	v_pk_fma_f32 v[204:205], v[148:149], v[92:93], v[156:157]
	v_pk_fma_f32 v[112:113], v[132:133], v[88:89], v[140:141]
	v_pk_fma_f32 v[206:207], v[150:151], v[94:95], v[158:159]
	v_pk_fma_f32 v[210:211], v[134:135], v[90:91], v[142:143]
	v_pk_fma_f32 v[204:205], v[152:153], v[172:173], v[204:205]
	v_pk_fma_f32 v[112:113], v[128:129], v[164:165], v[112:113]
	v_pk_fma_f32 v[206:207], v[154:155], v[174:175], v[206:207]
	v_pk_fma_f32 v[210:211], v[130:131], v[166:167], v[210:211]
	v_pk_fma_f32 v[204:205], v[144:145], v[176:177], v[204:205]
	v_pk_fma_f32 v[112:113], v[136:137], v[168:169], v[112:113]
	v_pk_fma_f32 v[206:207], v[146:147], v[178:179], v[206:207]
	v_pk_fma_f32 v[210:211], v[138:139], v[170:171], v[210:211]
	v_pk_mul_f32 v[226:227], v[204:205], v[126:127]
	v_pk_mul_f32 v[228:229], v[206:207], v[126:127]
	v_exp_f32_e32 v226, v226
	v_exp_f32_e32 v227, v227
	v_exp_f32_e32 v228, v228
	v_exp_f32_e32 v229, v229
	s_nop 0
	v_pk_add_f32 v[226:227], v[226:227], 1.0 op_sel_hi:[1,0]
	v_pk_add_f32 v[228:229], v[228:229], 1.0 op_sel_hi:[1,0]
	v_rcp_f32_e32 v226, v226
	v_rcp_f32_e32 v227, v227
	v_rcp_f32_e32 v228, v228
	v_rcp_f32_e32 v229, v229
	s_nop 0
	v_pk_mul_f32 v[204:205], v[204:205], v[226:227]
	v_pk_mul_f32 v[206:207], v[206:207], v[228:229]
	v_pk_mul_f32 v[204:205], v[204:205], v[112:113]
	v_pk_mul_f32 v[206:207], v[206:207], v[210:211]
	v_cvt_pk_bf16_f32 v92, v204, v205
	v_cvt_pk_bf16_f32 v93, v206, v207
	global_load_dwordx4 v[64:67], v244, s[36:37] offset:16
	v_mov_b32_e32 v172, 0
	v_mov_b32_e32 v173, 0
	v_mov_b32_e32 v174, 0
	v_mov_b32_e32 v175, 0
	v_mov_b32_e32 v164, 0
	v_mov_b32_e32 v165, 0
	v_mov_b32_e32 v166, 0
	v_mov_b32_e32 v167, 0
	v_mov_b32_e32 v176, 0
	v_mov_b32_e32 v177, 0
	v_mov_b32_e32 v178, 0
	v_mov_b32_e32 v179, 0
	v_mov_b32_e32 v168, 0
	v_mov_b32_e32 v169, 0
	v_mov_b32_e32 v170, 0
	v_mov_b32_e32 v171, 0
	s_andn2_b64 vcc, exec, s[24:25]
	s_cbranch_vccnz .Lupc2_nocarry10
	ds_read_b128 v[172:175], v215 offset:1040
	ds_read_b128 v[164:167], v215 offset:1552
	ds_read_b128 v[176:179], v215 offset:16
	ds_read_b128 v[168:171], v215 offset:528
; #define LAS __attribute__((address_space(3)))
;     __device__ __forceinline__ void operator()(const f32x4 (&acc)[2][2][4][2], const pg8::Unit& u, int wr, int wc, int fr, int fq) const {
;     ...
;         for (int n = 0; n < 2; ++n) {
;             const int jg = u.pn * 128 + cc0 + 4 * n;
;             const f32x4 g0w = *(const f32x4*)(cw + jg), g1w = *(const f32x4*)(cw + UPW + jg), g2w = *(const f32x4*)(cw + 2 * UPW + jg), gb = *(const f32x4*)(cb + jg);
;             const f32x4 u0w = *(const f32x4*)(cw + DFF + jg), u1w = *(const f32x4*)(cw + UPW + DFF + jg), u2w = *(const f32x4*)(cw + 2 * UPW + DFF + jg), ub = *(const f32x4*)(cb + DFF + jg);
; #pragma unroll
;             for (int ai = 0; ai < 2; ++ai) {
;                 const int gi = 2 * ai + wr;
;                 f32x4 pg1 = (f32x4){0.f, 0.f, 0.f, 0.f}, pg2 = pg1, pu1 = pg1, pu2 = pg1;
;                 if (gi > 0) {
;                     const LAS float* xp = xb + ((gi - 1) * 2) * 256 + cc0 + 4 * n;
;                     pg1 = *(const LAS f32x4*)(xp + 256); pu1 = *(const LAS f32x4*)(xp + 256 + 128);
;                     pg2 = *(const LAS f32x4*)(xp + (fr & 1) * 256); pu2 = *(const LAS f32x4*)(xp + (fr & 1) * 256 + 128);
;                 }
; #pragma unroll
;                 for (int m = 0; m < 4; ++m) {
;                     float a[4];
; #pragma unroll
;                     for (int e = 0; e < 4; ++e) {
;                         const float gc = acc[ai][0][m][n][e], uc = acc[ai][1][m][n][e];
;                         float og1, og2, ou1, ou2;
;                         if (m == 0) { og1 = pg1[e]; og2 = pg2[e]; ou1 = pu1[e]; ou2 = pu2[e]; }
;                         else { const float gp = acc[ai][0][m - 1][n][e], up = acc[ai][1][m - 1][n][e]; og1 = dpp_ror1(gp); og2 = dpp_ror2(gp); ou1 = dpp_ror1(up); ou2 = dpp_ror2(up); }
;                         const float gm1 = dpp_shr1(og1, gc), gm2 = dpp_shr2(og2, gc), um1 = dpp_shr1(ou1, uc), um2 = dpp_shr2(ou2, uc);
;                         const float yg = g0w[e] * gm2 + g1w[e] * gm1 + g2w[e] * gc + gb[e];
;                         const float yu = u0w[e] * um2 + u1w[e] * um1 + u2w[e] * uc + ub[e];
;                         a[e] = fast_silu(yg) * yu;
;                     }
;                     u32x2 pk; pk.x = cvt_pk_bf16(a[0], a[1]); pk.y = cvt_pk_bf16(a[2], a[3]);
;                     if (n == 0) lo[ai][m] = pk;
;                     else {
.Lupc2_nocarry10:
	s_waitcnt vmcnt(1) lgkmcnt(0)
	v_mov_b32_dpp v172, v40 row_shr:1 row_mask:0xf bank_mask:0xf
	v_mov_b32_dpp v176, v44 row_shr:1 row_mask:0xf bank_mask:0xf
	v_mov_b32_dpp v164, v32 row_shr:1 row_mask:0xf bank_mask:0xf
	v_mov_b32_dpp v168, v36 row_shr:1 row_mask:0xf bank_mask:0xf
	v_mov_b32_dpp v173, v41 row_shr:1 row_mask:0xf bank_mask:0xf
	v_mov_b32_dpp v177, v45 row_shr:1 row_mask:0xf bank_mask:0xf
	v_mov_b32_dpp v165, v33 row_shr:1 row_mask:0xf bank_mask:0xf
	v_mov_b32_dpp v169, v37 row_shr:1 row_mask:0xf bank_mask:0xf
	v_mov_b32_dpp v174, v42 row_shr:1 row_mask:0xf bank_mask:0xf
	v_mov_b32_dpp v178, v46 row_shr:1 row_mask:0xf bank_mask:0xf
	v_mov_b32_dpp v166, v34 row_shr:1 row_mask:0xf bank_mask:0xf
	v_mov_b32_dpp v170, v38 row_shr:1 row_mask:0xf bank_mask:0xf
	v_mov_b32_dpp v175, v43 row_shr:1 row_mask:0xf bank_mask:0xf
	v_mov_b32_dpp v179, v47 row_shr:1 row_mask:0xf bank_mask:0xf
	v_mov_b32_dpp v167, v35 row_shr:1 row_mask:0xf bank_mask:0xf
	v_mov_b32_dpp v171, v39 row_shr:1 row_mask:0xf bank_mask:0xf
	v_pk_fma_f32 v[204:205], v[114:115], v[40:41], v[118:119]
	v_pk_fma_f32 v[112:113], v[100:101], v[32:33], v[96:97]
	v_pk_fma_f32 v[206:207], v[116:117], v[42:43], v[120:121]
	v_pk_fma_f32 v[210:211], v[102:103], v[34:35], v[98:99]
	v_pk_fma_f32 v[204:205], v[230:231], v[44:45], v[204:205]
	v_pk_fma_f32 v[112:113], v[234:235], v[36:37], v[112:113]
	v_pk_fma_f32 v[206:207], v[232:233], v[46:47], v[206:207]
	v_pk_fma_f32 v[210:211], v[236:237], v[38:39], v[210:211]
	s_waitcnt vmcnt(0)
	v_pk_fma_f32 v[204:205], v[238:239], v[52:53], v[204:205]
	v_pk_fma_f32 v[112:113], v[64:65], v[48:49], v[112:113]
	v_pk_fma_f32 v[206:207], v[240:241], v[54:55], v[206:207]
	v_pk_fma_f32 v[210:211], v[66:67], v[50:51], v[210:211]
	v_pk_mul_f32 v[226:227], v[204:205], v[126:127]
	v_pk_mul_f32 v[228:229], v[206:207], v[126:127]
	v_exp_f32_e32 v226, v226
	v_exp_f32_e32 v227, v227
	v_exp_f32_e32 v228, v228
	v_exp_f32_e32 v229, v229
	s_nop 0
	v_pk_add_f32 v[226:227], v[226:227], 1.0 op_sel_hi:[1,0]
	v_pk_add_f32 v[228:229], v[228:229], 1.0 op_sel_hi:[1,0]
	v_rcp_f32_e32 v226, v226
	v_rcp_f32_e32 v227, v227
	v_rcp_f32_e32 v228, v228
	v_rcp_f32_e32 v229, v229
	s_nop 0
	v_pk_mul_f32 v[204:205], v[204:205], v[226:227]
	v_pk_mul_f32 v[206:207], v[206:207], v[228:229]
	v_pk_mul_f32 v[204:205], v[204:205], v[112:113]
	v_pk_mul_f32 v[206:207], v[206:207], v[210:211]
	v_cvt_pk_bf16_f32 v106, v204, v205
	v_cvt_pk_bf16_f32 v107, v206, v207
	v_add_u32_e32 v242, 0x8400, v243
	global_store_dwordx4 v242, v[104:107], s[14:15] nt
	v_pk_fma_f32 v[204:205], v[114:115], v[44:45], v[118:119]
	v_pk_fma_f32 v[112:113], v[100:101], v[36:37], v[96:97]
	v_pk_fma_f32 v[206:207], v[116:117], v[46:47], v[120:121]
	v_pk_fma_f32 v[210:211], v[102:103], v[38:39], v[98:99]
	v_pk_fma_f32 v[204:205], v[230:231], v[52:53], v[204:205]
	v_pk_fma_f32 v[112:113], v[234:235], v[48:49], v[112:113]
	v_pk_fma_f32 v[206:207], v[232:233], v[54:55], v[206:207]
	v_pk_fma_f32 v[210:211], v[236:237], v[50:51], v[210:211]
	v_pk_fma_f32 v[204:205], v[238:239], v[60:61], v[204:205]
	v_pk_fma_f32 v[112:113], v[64:65], v[56:57], v[112:113]
	v_pk_fma_f32 v[206:207], v[240:241], v[62:63], v[206:207]
	v_pk_fma_f32 v[210:211], v[66:67], v[58:59], v[210:211]
	v_pk_mul_f32 v[226:227], v[204:205], v[126:127]
	v_pk_mul_f32 v[228:229], v[206:207], v[126:127]
	v_exp_f32_e32 v226, v226
	v_exp_f32_e32 v227, v227
	v_exp_f32_e32 v228, v228
	v_exp_f32_e32 v229, v229
	s_nop 0
	v_pk_add_f32 v[226:227], v[226:227], 1.0 op_sel_hi:[1,0]
	v_pk_add_f32 v[228:229], v[228:229], 1.0 op_sel_hi:[1,0]
	v_rcp_f32_e32 v226, v226
	v_rcp_f32_e32 v227, v227
	v_rcp_f32_e32 v228, v228
	v_rcp_f32_e32 v229, v229
	s_nop 0
	v_pk_mul_f32 v[204:205], v[204:205], v[226:227]
	v_pk_mul_f32 v[206:207], v[206:207], v[228:229]
	v_pk_mul_f32 v[204:205], v[204:205], v[112:113]
	v_pk_mul_f32 v[206:207], v[206:207], v[210:211]
	v_cvt_pk_bf16_f32 v110, v204, v205
	v_cvt_pk_bf16_f32 v111, v206, v207
	v_add_u32_e32 v242, 0x5800, v243
	global_store_dwordx4 v242, v[108:111], s[14:15] nt
	v_pk_fma_f32 v[204:205], v[114:115], v[52:53], v[118:119]
	v_pk_fma_f32 v[112:113], v[100:101], v[48:49], v[96:97]
	v_pk_fma_f32 v[206:207], v[116:117], v[54:55], v[120:121]
	v_pk_fma_f32 v[210:211], v[102:103], v[50:51], v[98:99]
	v_pk_fma_f32 v[204:205], v[230:231], v[60:61], v[204:205]
	v_pk_fma_f32 v[112:113], v[234:235], v[56:57], v[112:113]
	v_pk_fma_f32 v[206:207], v[232:233], v[62:63], v[206:207]
	v_pk_fma_f32 v[210:211], v[236:237], v[58:59], v[210:211]
	v_pk_fma_f32 v[204:205], v[238:239], v[172:173], v[204:205]
	v_pk_fma_f32 v[112:113], v[64:65], v[164:165], v[112:113]
	v_pk_fma_f32 v[206:207], v[240:241], v[174:175], v[206:207]
	v_pk_fma_f32 v[210:211], v[66:67], v[166:167], v[210:211]
	v_pk_mul_f32 v[226:227], v[204:205], v[126:127]
	v_pk_mul_f32 v[228:229], v[206:207], v[126:127]
	v_exp_f32_e32 v226, v226
	v_exp_f32_e32 v227, v227
	v_exp_f32_e32 v228, v228
	v_exp_f32_e32 v229, v229
	s_nop 0
	v_pk_add_f32 v[226:227], v[226:227], 1.0 op_sel_hi:[1,0]
	v_pk_add_f32 v[228:229], v[228:229], 1.0 op_sel_hi:[1,0]
	v_rcp_f32_e32 v226, v226
	v_rcp_f32_e32 v227, v227
	v_rcp_f32_e32 v228, v228
	v_rcp_f32_e32 v229, v229
	s_nop 0
	v_pk_mul_f32 v[204:205], v[204:205], v[226:227]
	v_pk_mul_f32 v[206:207], v[206:207], v[228:229]
	v_pk_mul_f32 v[204:205], v[204:205], v[112:113]
	v_pk_mul_f32 v[206:207], v[206:207], v[210:211]
	v_cvt_pk_bf16_f32 v124, v204, v205
	v_cvt_pk_bf16_f32 v125, v206, v207
	v_add_u32_e32 v242, 0x2c00, v243
	s_and_saveexec_b64 s[8:9], s[78:79]
	global_store_dwordx4 v242, v[122:125], s[14:15] nt
	s_or_b64 exec, exec, s[8:9]
; __device__ __forceinline__ unsigned cvt_pk_bf16(float lo, float hi) { unsigned r; asm volatile("v_cvt_pk_bf16_f32 %0, %1, %2" : "=v"(r) : "v"(lo), "v"(hi)); return r; }
; __device__ __forceinline__ float fast_silu(float x) { return x * fast_sigmoid(x); }
; __device__ __forceinline__ float dpp_shr1(float old, float src) { return __int_as_float(__builtin_amdgcn_update_dpp(__float_as_int(old), __float_as_int(src), 0x111, 0xf, 0xf, false)); }
; __device__ __forceinline__ float dpp_shr2(float old, float src) { return __int_as_float(__builtin_amdgcn_update_dpp(__float_as_int(old), __float_as_int(src), 0x112, 0xf, 0xf, false)); }
; __device__ __forceinline__ float dpp_ror1(float src) { return __int_as_float(__builtin_amdgcn_mov_dpp(__float_as_int(src), 0x121, 0xf, 0xf, true)); }
;     __device__ __forceinline__ void operator()(const f32x4 (&acc)[2][2][4][2], const pg8::Unit& u, int wr, int wc, int fr, int fq) const {
;     ...
; #pragma unroll
;                 for (int m = 0; m < 4; ++m) {
;                     float a[4];
; #pragma unroll
;                     for (int e = 0; e < 4; ++e) {
;                         const float gc = acc[ai][0][m][n][e], uc = acc[ai][1][m][n][e];
;                         float og1, og2, ou1, ou2;
;                         if (m == 0) { og1 = pg1[e]; og2 = pg2[e]; ou1 = pu1[e]; ou2 = pu2[e]; }
;                         else { const float gp = acc[ai][0][m - 1][n][e], up = acc[ai][1][m - 1][n][e]; og1 = dpp_ror1(gp); og2 = dpp_ror2(gp); ou1 = dpp_ror1(up); ou2 = dpp_ror2(up); }
;                         const float gm1 = dpp_shr1(og1, gc), gm2 = dpp_shr2(og2, gc), um1 = dpp_shr1(ou1, uc), um2 = dpp_shr2(ou2, uc);
;                         const float yg = g0w[e] * gm2 + g1w[e] * gm1 + g2w[e] * gc + gb[e];
;                         const float yu = u0w[e] * um2 + u1w[e] * um1 + u2w[e] * uc + ub[e];
;                         a[e] = fast_silu(yg) * yu;
;                     }
;                     u32x2 pk; pk.x = cvt_pk_bf16(a[0], a[1]); pk.y = cvt_pk_bf16(a[2], a[3]);
;                     if (n == 0) lo[ai][m] = pk;
;                     else {
;                         const bool skip = (gi == 0) && (m == 0) && (fr < 2);
;                         if (!skip) __builtin_nontemporal_store((u32x4){lo[ai][m].x, lo[ai][m].y, pk.x, pk.y}, (u32x4*)(ACT + (size_t)(row0 + ai * 128 + m * 16) * DFF + u.pn * 128 + cc0));
;                     }
	v_pk_fma_f32 v[204:205], v[114:115], v[60:61], v[118:119]
	v_pk_fma_f32 v[112:113], v[100:101], v[56:57], v[96:97]
	v_pk_fma_f32 v[206:207], v[116:117], v[62:63], v[120:121]
	v_pk_fma_f32 v[210:211], v[102:103], v[58:59], v[98:99]
	v_pk_fma_f32 v[204:205], v[230:231], v[172:173], v[204:205]
	v_pk_fma_f32 v[112:113], v[234:235], v[164:165], v[112:113]
	v_pk_fma_f32 v[206:207], v[232:233], v[174:175], v[206:207]
	v_pk_fma_f32 v[210:211], v[236:237], v[166:167], v[210:211]
	v_pk_fma_f32 v[204:205], v[238:239], v[176:177], v[204:205]
	v_pk_fma_f32 v[112:113], v[64:65], v[168:169], v[112:113]
	v_pk_fma_f32 v[206:207], v[240:241], v[178:179], v[206:207]
	v_pk_fma_f32 v[210:211], v[66:67], v[170:171], v[210:211]
	v_pk_mul_f32 v[226:227], v[204:205], v[126:127]
	v_pk_mul_f32 v[228:229], v[206:207], v[126:127]
	v_exp_f32_e32 v226, v226
	v_exp_f32_e32 v227, v227
	v_exp_f32_e32 v228, v228
	v_exp_f32_e32 v229, v229
	s_nop 0
	v_pk_add_f32 v[226:227], v[226:227], 1.0 op_sel_hi:[1,0]
	v_pk_add_f32 v[228:229], v[228:229], 1.0 op_sel_hi:[1,0]
	v_rcp_f32_e32 v226, v226
	v_rcp_f32_e32 v227, v227
	v_rcp_f32_e32 v228, v228
	v_rcp_f32_e32 v229, v229
	s_nop 0
	v_pk_mul_f32 v[204:205], v[204:205], v[226:227]
	v_pk_mul_f32 v[206:207], v[206:207], v[228:229]
	v_pk_mul_f32 v[204:205], v[204:205], v[112:113]
	v_pk_mul_f32 v[206:207], v[206:207], v[210:211]
	v_cvt_pk_bf16_f32 v162, v204, v205
	v_cvt_pk_bf16_f32 v163, v206, v207
	v_mov_b32_e32 v242, v243
	s_and_saveexec_b64 s[8:9], s[78:79]
	global_store_dwordx4 v242, v[160:163], s[14:15] nt
	s_or_b64 exec, exec, s[8:9]
	ds_read_b128 v[172:175], v215 offset:5136
	ds_read_b128 v[164:167], v215 offset:5648
	ds_read_b128 v[176:179], v215 offset:4112
	ds_read_b128 v[168:171], v215 offset:4624
	s_waitcnt lgkmcnt(0)
	v_mov_b32_dpp v172, v8 row_shr:1 row_mask:0xf bank_mask:0xf
	v_mov_b32_dpp v176, v12 row_shr:1 row_mask:0xf bank_mask:0xf
	v_mov_b32_dpp v164, v0 row_shr:1 row_mask:0xf bank_mask:0xf
	v_mov_b32_dpp v168, v4 row_shr:1 row_mask:0xf bank_mask:0xf
	v_mov_b32_dpp v173, v9 row_shr:1 row_mask:0xf bank_mask:0xf
	v_mov_b32_dpp v177, v13 row_shr:1 row_mask:0xf bank_mask:0xf
	v_mov_b32_dpp v165, v1 row_shr:1 row_mask:0xf bank_mask:0xf
	v_mov_b32_dpp v169, v5 row_shr:1 row_mask:0xf bank_mask:0xf
	v_mov_b32_dpp v174, v10 row_shr:1 row_mask:0xf bank_mask:0xf
	v_mov_b32_dpp v178, v14 row_shr:1 row_mask:0xf bank_mask:0xf
	v_mov_b32_dpp v166, v2 row_shr:1 row_mask:0xf bank_mask:0xf
	v_mov_b32_dpp v170, v6 row_shr:1 row_mask:0xf bank_mask:0xf
	v_mov_b32_dpp v175, v11 row_shr:1 row_mask:0xf bank_mask:0xf
	v_mov_b32_dpp v179, v15 row_shr:1 row_mask:0xf bank_mask:0xf
	v_mov_b32_dpp v167, v3 row_shr:1 row_mask:0xf bank_mask:0xf
	v_mov_b32_dpp v171, v7 row_shr:1 row_mask:0xf bank_mask:0xf
	v_pk_fma_f32 v[204:205], v[114:115], v[8:9], v[118:119]
	v_pk_fma_f32 v[112:113], v[100:101], v[0:1], v[96:97]
	v_pk_fma_f32 v[206:207], v[116:117], v[10:11], v[120:121]
	v_pk_fma_f32 v[210:211], v[102:103], v[2:3], v[98:99]
	v_pk_fma_f32 v[204:205], v[230:231], v[12:13], v[204:205]
	v_pk_fma_f32 v[112:113], v[234:235], v[4:5], v[112:113]
	v_pk_fma_f32 v[206:207], v[232:233], v[14:15], v[206:207]
	v_pk_fma_f32 v[210:211], v[236:237], v[6:7], v[210:211]
	v_pk_fma_f32 v[204:205], v[238:239], v[20:21], v[204:205]
	v_pk_fma_f32 v[112:113], v[64:65], v[16:17], v[112:113]
	v_pk_fma_f32 v[206:207], v[240:241], v[22:23], v[206:207]
	v_pk_fma_f32 v[210:211], v[66:67], v[18:19], v[210:211]
	v_pk_mul_f32 v[226:227], v[204:205], v[126:127]
	v_pk_mul_f32 v[228:229], v[206:207], v[126:127]
	v_exp_f32_e32 v226, v226
	v_exp_f32_e32 v227, v227
	v_exp_f32_e32 v228, v228
	v_exp_f32_e32 v229, v229
	s_nop 0
	v_pk_add_f32 v[226:227], v[226:227], 1.0 op_sel_hi:[1,0]
	v_pk_add_f32 v[228:229], v[228:229], 1.0 op_sel_hi:[1,0]
	v_rcp_f32_e32 v226, v226
	v_rcp_f32_e32 v227, v227
	v_rcp_f32_e32 v228, v228
	v_rcp_f32_e32 v229, v229
	s_nop 0
	v_pk_mul_f32 v[204:205], v[204:205], v[226:227]
	v_pk_mul_f32 v[206:207], v[206:207], v[228:229]
	v_pk_mul_f32 v[204:205], v[204:205], v[112:113]
	v_pk_mul_f32 v[206:207], v[206:207], v[210:211]
	v_cvt_pk_bf16_f32 v74, v204, v205
	v_cvt_pk_bf16_f32 v75, v206, v207
	v_add_u32_e32 v242, 0x168400, v243
	global_store_dwordx4 v242, v[72:75], s[14:15] nt
	v_pk_fma_f32 v[204:205], v[114:115], v[12:13], v[118:119]
	v_pk_fma_f32 v[112:113], v[100:101], v[4:5], v[96:97]
	v_pk_fma_f32 v[206:207], v[116:117], v[14:15], v[120:121]
	v_pk_fma_f32 v[210:211], v[102:103], v[6:7], v[98:99]
; __device__ __forceinline__ unsigned cvt_pk_bf16(float lo, float hi) { unsigned r; asm volatile("v_cvt_pk_bf16_f32 %0, %1, %2" : "=v"(r) : "v"(lo), "v"(hi)); return r; }
; __device__ __forceinline__ float fast_silu(float x) { return x * fast_sigmoid(x); }
; __device__ __forceinline__ float dpp_shr1(float old, float src) { return __int_as_float(__builtin_amdgcn_update_dpp(__float_as_int(old), __float_as_int(src), 0x111, 0xf, 0xf, false)); }
; __device__ __forceinline__ float dpp_shr2(float old, float src) { return __int_as_float(__builtin_amdgcn_update_dpp(__float_as_int(old), __float_as_int(src), 0x112, 0xf, 0xf, false)); }
; __device__ __forceinline__ float dpp_ror1(float src) { return __int_as_float(__builtin_amdgcn_mov_dpp(__float_as_int(src), 0x121, 0xf, 0xf, true)); }
;     __device__ __forceinline__ void operator()(const f32x4 (&acc)[2][2][4][2], const pg8::Unit& u, int wr, int wc, int fr, int fq) const {
;     ...
;                 for (int m = 0; m < 4; ++m) {
;                     float a[4];
; #pragma unroll
;                     for (int e = 0; e < 4; ++e) {
;                         const float gc = acc[ai][0][m][n][e], uc = acc[ai][1][m][n][e];
;                         float og1, og2, ou1, ou2;
;                         if (m == 0) { og1 = pg1[e]; og2 = pg2[e]; ou1 = pu1[e]; ou2 = pu2[e]; }
;                         else { const float gp = acc[ai][0][m - 1][n][e], up = acc[ai][1][m - 1][n][e]; og1 = dpp_ror1(gp); og2 = dpp_ror2(gp); ou1 = dpp_ror1(up); ou2 = dpp_ror2(up); }
;                         const float gm1 = dpp_shr1(og1, gc), gm2 = dpp_shr2(og2, gc), um1 = dpp_shr1(ou1, uc), um2 = dpp_shr2(ou2, uc);
;                         const float yg = g0w[e] * gm2 + g1w[e] * gm1 + g2w[e] * gc + gb[e];
;                         const float yu = u0w[e] * um2 + u1w[e] * um1 + u2w[e] * uc + ub[e];
;                         a[e] = fast_silu(yg) * yu;
;                     }
;                     u32x2 pk; pk.x = cvt_pk_bf16(a[0], a[1]); pk.y = cvt_pk_bf16(a[2], a[3]);
;                     if (n == 0) lo[ai][m] = pk;
;                     else {
;                         const bool skip = (gi == 0) && (m == 0) && (fr < 2);
;                         if (!skip) __builtin_nontemporal_store((u32x4){lo[ai][m].x, lo[ai][m].y, pk.x, pk.y}, (u32x4*)(ACT + (size_t)(row0 + ai * 128 + m * 16) * DFF + u.pn * 128 + cc0));
;                     }
	v_pk_fma_f32 v[204:205], v[230:231], v[20:21], v[204:205]
	v_pk_fma_f32 v[112:113], v[234:235], v[16:17], v[112:113]
	v_pk_fma_f32 v[206:207], v[232:233], v[22:23], v[206:207]
	v_pk_fma_f32 v[210:211], v[236:237], v[18:19], v[210:211]
	v_pk_fma_f32 v[204:205], v[238:239], v[28:29], v[204:205]
	v_pk_fma_f32 v[112:113], v[64:65], v[24:25], v[112:113]
	v_pk_fma_f32 v[206:207], v[240:241], v[30:31], v[206:207]
	v_pk_fma_f32 v[210:211], v[66:67], v[26:27], v[210:211]
	v_pk_mul_f32 v[226:227], v[204:205], v[126:127]
	v_pk_mul_f32 v[228:229], v[206:207], v[126:127]
	v_exp_f32_e32 v226, v226
	v_exp_f32_e32 v227, v227
	v_exp_f32_e32 v228, v228
	v_exp_f32_e32 v229, v229
	s_nop 0
	v_pk_add_f32 v[226:227], v[226:227], 1.0 op_sel_hi:[1,0]
	v_pk_add_f32 v[228:229], v[228:229], 1.0 op_sel_hi:[1,0]
	v_rcp_f32_e32 v226, v226
	v_rcp_f32_e32 v227, v227
	v_rcp_f32_e32 v228, v228
	v_rcp_f32_e32 v229, v229
	s_nop 0
	v_pk_mul_f32 v[204:205], v[204:205], v[226:227]
	v_pk_mul_f32 v[206:207], v[206:207], v[228:229]
	v_pk_mul_f32 v[204:205], v[204:205], v[112:113]
	v_pk_mul_f32 v[206:207], v[206:207], v[210:211]
	v_cvt_pk_bf16_f32 v78, v204, v205
	v_cvt_pk_bf16_f32 v79, v206, v207
	v_add_u32_e32 v242, 0x165800, v243
	global_store_dwordx4 v242, v[76:79], s[14:15] nt
	v_pk_fma_f32 v[204:205], v[114:115], v[20:21], v[118:119]
	v_pk_fma_f32 v[112:113], v[100:101], v[16:17], v[96:97]
	v_pk_fma_f32 v[206:207], v[116:117], v[22:23], v[120:121]
	v_pk_fma_f32 v[210:211], v[102:103], v[18:19], v[98:99]
	v_pk_fma_f32 v[204:205], v[230:231], v[28:29], v[204:205]
	v_pk_fma_f32 v[112:113], v[234:235], v[24:25], v[112:113]
	v_pk_fma_f32 v[206:207], v[232:233], v[30:31], v[206:207]
	v_pk_fma_f32 v[210:211], v[236:237], v[26:27], v[210:211]
	v_pk_fma_f32 v[204:205], v[238:239], v[172:173], v[204:205]
	v_pk_fma_f32 v[112:113], v[64:65], v[164:165], v[112:113]
	v_pk_fma_f32 v[206:207], v[240:241], v[174:175], v[206:207]
	v_pk_fma_f32 v[210:211], v[66:67], v[166:167], v[210:211]
	v_pk_mul_f32 v[226:227], v[204:205], v[126:127]
	v_pk_mul_f32 v[228:229], v[206:207], v[126:127]
	v_exp_f32_e32 v226, v226
	v_exp_f32_e32 v227, v227
	v_exp_f32_e32 v228, v228
	v_exp_f32_e32 v229, v229
	s_nop 0
	v_pk_add_f32 v[226:227], v[226:227], 1.0 op_sel_hi:[1,0]
	v_pk_add_f32 v[228:229], v[228:229], 1.0 op_sel_hi:[1,0]
	v_rcp_f32_e32 v226, v226
	v_rcp_f32_e32 v227, v227
	v_rcp_f32_e32 v228, v228
	v_rcp_f32_e32 v229, v229
	s_nop 0
	v_pk_mul_f32 v[204:205], v[204:205], v[226:227]
	v_pk_mul_f32 v[206:207], v[206:207], v[228:229]
	v_pk_mul_f32 v[204:205], v[204:205], v[112:113]
	v_pk_mul_f32 v[206:207], v[206:207], v[210:211]
	v_cvt_pk_bf16_f32 v86, v204, v205
	v_cvt_pk_bf16_f32 v87, v206, v207
	v_add_u32_e32 v242, 0x162c00, v243
	global_store_dwordx4 v242, v[84:87], s[14:15] nt
	v_pk_fma_f32 v[204:205], v[114:115], v[28:29], v[118:119]
	v_pk_fma_f32 v[112:113], v[100:101], v[24:25], v[96:97]
	v_pk_fma_f32 v[206:207], v[116:117], v[30:31], v[120:121]
	v_pk_fma_f32 v[210:211], v[102:103], v[26:27], v[98:99]
	v_pk_fma_f32 v[204:205], v[230:231], v[172:173], v[204:205]
	v_pk_fma_f32 v[112:113], v[234:235], v[164:165], v[112:113]
	v_pk_fma_f32 v[206:207], v[232:233], v[174:175], v[206:207]
	v_pk_fma_f32 v[210:211], v[236:237], v[166:167], v[210:211]
	v_pk_fma_f32 v[204:205], v[238:239], v[176:177], v[204:205]
	v_pk_fma_f32 v[112:113], v[64:65], v[168:169], v[112:113]
	v_pk_fma_f32 v[206:207], v[240:241], v[178:179], v[206:207]
	v_pk_fma_f32 v[210:211], v[66:67], v[170:171], v[210:211]
	v_pk_mul_f32 v[226:227], v[204:205], v[126:127]
	v_pk_mul_f32 v[228:229], v[206:207], v[126:127]
	v_exp_f32_e32 v226, v226
	v_exp_f32_e32 v227, v227
	v_exp_f32_e32 v228, v228
	v_exp_f32_e32 v229, v229
	s_nop 0
	v_pk_add_f32 v[226:227], v[226:227], 1.0 op_sel_hi:[1,0]
	v_pk_add_f32 v[228:229], v[228:229], 1.0 op_sel_hi:[1,0]
	v_rcp_f32_e32 v226, v226
	v_rcp_f32_e32 v227, v227
	v_rcp_f32_e32 v228, v228
	v_rcp_f32_e32 v229, v229
	s_nop 0
	v_pk_mul_f32 v[204:205], v[204:205], v[226:227]
	v_pk_mul_f32 v[206:207], v[206:207], v[228:229]
	v_pk_mul_f32 v[204:205], v[204:205], v[112:113]
	v_pk_mul_f32 v[206:207], v[206:207], v[210:211]
	v_cvt_pk_bf16_f32 v94, v204, v205
	v_cvt_pk_bf16_f32 v95, v206, v207
	v_add_u32_e32 v242, 0x160000, v243
	global_store_dwordx4 v242, v[92:95], s[14:15] nt
	s_andn2_b64 vcc, exec, s[4:5]
	s_mov_b64 s[4:5], -1
	s_cbranch_vccnz .LBB0_924
	s_and_b64 vcc, exec, s[6:7]
	s_cbranch_vccnz .LBB0_923
	s_barrier
	s_branch .LBB0_923
